# attention main loop: P.V MFMAs as accumulator pairs with the P fragment alternating between two registers (instead of 4-long chains); GEMM snake order unchanged; bit-identical
# speedup vs baseline: 1.0120x; 1.0007x over previous
.LBB0_1309:
	s_waitcnt lgkmcnt(7)
	v_mfma_f32_32x32x16_bf16 v[114:129], v[190:193], v[150:153], 0
	v_add_f32_e32 v98, v82, v83
	v_add_f32_e32 v98, v84, v98
	v_add_f32_e32 v98, v85, v98
	v_add_f32_e32 v98, v86, v98
	v_add_u32_e32 v247, s30, v246
	v_add_f32_e32 v98, v87, v98
	v_cvt_pk_bf16_f32 v158, v82, v83
	v_cvt_pk_bf16_f32 v159, v84, v85
	s_nop 0
	v_add_f32_e32 v82, v88, v98
	s_waitcnt lgkmcnt(6)
	v_mfma_f32_32x32x16_bf16 v[98:113], v[182:185], v[150:153], 0
	v_add_f32_e32 v82, v89, v82
	v_add_f32_e32 v82, v90, v82
	v_add_f32_e32 v82, v91, v82
	v_cvt_pk_bf16_f32 v160, v86, v87
	v_cvt_pk_bf16_f32 v161, v88, v89
	s_waitcnt lgkmcnt(5)
	v_mfma_f32_32x32x16_bf16 v[114:129], v[186:189], v[146:149], v[114:129]
	v_add_f32_e32 v82, v92, v82
	v_add_f32_e32 v82, v93, v82
	v_add_f32_e32 v82, v94, v82
	v_add_f32_e32 v82, v95, v82
	v_cvt_pk_bf16_f32 v154, v90, v91
	v_cvt_pk_bf16_f32 v155, v92, v93
	s_waitcnt lgkmcnt(4)
	v_mfma_f32_32x32x16_bf16 v[98:113], v[178:181], v[146:149], v[98:113]
	v_add_f32_e32 v82, v96, v82
	v_add_f32_e32 v82, v97, v82
	v_add_f32_e32 v82, v66, v82
	v_add_f32_e32 v86, v67, v82
	v_cvt_pk_bf16_f32 v156, v94, v95
	v_cvt_pk_bf16_f32 v157, v96, v97
	ds_read_b64_tr_b16 v[82:83], v247 offset:49152
	ds_read_b64_tr_b16 v[84:85], v247 offset:49664
	s_waitcnt lgkmcnt(5)
	v_mfma_f32_32x32x16_bf16 v[114:129], v[174:177], v[142:145], v[114:129]
	v_add_f32_e32 v86, v68, v86
	v_add_f32_e32 v86, v69, v86
	v_add_f32_e32 v86, v70, v86
	v_add_f32_e32 v86, v71, v86
	v_cvt_pk_bf16_f32 v138, v66, v67
	v_cvt_pk_bf16_f32 v139, v68, v69
	ds_read_b64_tr_b16 v[66:67], v247 offset:50176
	ds_read_b64_tr_b16 v[68:69], v247 offset:50688
	s_waitcnt lgkmcnt(6)
	v_mfma_f32_32x32x16_bf16 v[98:113], v[170:173], v[142:145], v[98:113]
	v_add_f32_e32 v86, v72, v86
	v_add_f32_e32 v86, v73, v86
	v_add_f32_e32 v86, v74, v86
	v_add_f32_e32 v86, v75, v86
	v_cvt_pk_bf16_f32 v140, v70, v71
	v_cvt_pk_bf16_f32 v141, v72, v73
	ds_read_b64_tr_b16 v[70:71], v247 offset:53248
	ds_read_b64_tr_b16 v[72:73], v247 offset:53760
	s_waitcnt lgkmcnt(7)
	v_mfma_f32_32x32x16_bf16 v[114:129], v[166:169], v[134:137], v[114:129]
	v_add_f32_e32 v86, v76, v86
	v_add_f32_e32 v86, v77, v86
	v_add_f32_e32 v86, v78, v86
	v_add_f32_e32 v86, v79, v86
	v_cvt_pk_bf16_f32 v130, v74, v75
	v_cvt_pk_bf16_f32 v131, v76, v77
	ds_read_b64_tr_b16 v[74:75], v247 offset:54272
	ds_read_b64_tr_b16 v[76:77], v247 offset:54784
	s_waitcnt lgkmcnt(8)
	v_mfma_f32_32x32x16_bf16 v[98:113], v[162:165], v[134:137], v[98:113]
	v_add_f32_e32 v86, v80, v86
	v_add_f32_e32 v86, v81, v86
	v_add_f32_e32 v86, 0, v86
	v_cvt_pk_bf16_f32 v132, v78, v79
	v_cvt_pk_bf16_f32 v133, v80, v81
	v_lshl_add_u64 v[188:189], v[214:215], 0, s[52:53]
	v_lshl_add_u64 v[78:79], v[188:189], 0, s[70:71]
	s_add_i32 s27, s91, s25
	s_mov_b32 s30, m0
	s_mov_b32 m0, s27
	s_nop 0
	global_load_lds_dwordx4 v[78:79], off
	s_mov_b32 m0, s30
	v_lshl_add_u64 v[78:79], v[188:189], 0, s[72:73]
	v_lshl_add_u64 v[186:187], v[216:217], 0, s[52:53]
	s_addk_i32 s27, 0x2000
	s_mov_b32 s30, m0
	s_mov_b32 m0, s27
	s_nop 0
	global_load_lds_dwordx4 v[78:79], off
	s_mov_b32 m0, s30
	v_lshl_add_u64 v[78:79], v[186:187], 0, s[74:75]
	s_add_i32 s27, s29, s24
	s_mov_b32 s30, m0
	s_mov_b32 m0, s27
	s_nop 0
	global_load_lds_dwordx4 v[78:79], off
	s_mov_b32 m0, s30
	v_lshl_add_u64 v[78:79], v[186:187], 0, s[76:77]
	s_addk_i32 s27, 0x2000
	s_mov_b32 s30, m0
	s_mov_b32 m0, s27
	s_nop 0
	global_load_lds_dwordx4 v[78:79], off
	s_mov_b32 m0, s30
	v_max_f32_e32 v78, v115, v115
	v_max_f32_e32 v79, v114, v114
	v_max_f32_e32 v78, v79, v78
	v_max3_f32 v79, v116, v117, v99
	v_max3_f32 v78, v78, v98, v100
	v_max3_f32 v78, v78, v101, v118
	v_max3_f32 v79, v79, v120, v121
	v_max3_f32 v78, v78, v119, v102
	v_max3_f32 v79, v79, v104, v105
	v_max3_f32 v78, v78, v103, v122
	v_max3_f32 v79, v79, v124, v125
	v_max3_f32 v78, v78, v123, v106
	v_max3_f32 v79, v79, v108, v109
	v_max3_f32 v78, v78, v107, v126
	v_max3_f32 v79, v79, v128, v129
	v_max3_f32 v78, v78, v127, v110
	v_max3_f32 v79, v79, v112, v113
	v_max3_f32 v78, v78, v111, v79
	v_mov_b32_e32 v79, v78
	s_nop 1
	v_permlane32_swap_b32_e32 v78, v79
	v_max_f32_e32 v79, v79, v79
	v_max_f32_e32 v78, v78, v78
	v_max_f32_e32 v78, v78, v79
	v_sub_f32_e32 v78, v78, v243
	v_cmp_lt_f32_e32 vcc, s93, v78
	s_cmp_lg_u64 vcc, 0
	v_add_f32_e32 v190, v250, v86
	s_cselect_b64 s[36:37], -1, 0
	s_cbranch_vccnz .LBB0_1317
.LBB0_1310:
	s_waitcnt lgkmcnt(6)
	v_mfma_f32_32x32x16_bf16 v[18:33], v[158:161], v[82:85], v[18:33]
	v_sub_f32_e32 v78, v114, v243
	v_exp_f32_e32 v114, v78
	v_sub_f32_e32 v78, v115, v243
	v_exp_f32_e32 v115, v78
	ds_read_b64_tr_b16 v[78:79], v247 offset:57344
	ds_read_b64_tr_b16 v[80:81], v247 offset:57856
	s_waitcnt lgkmcnt(6)
	v_mfma_f32_32x32x16_bf16 v[18:33], v[154:157], v[66:69], v[18:33]
	v_sub_f32_e32 v66, v116, v243
	v_exp_f32_e32 v116, v66
	v_sub_f32_e32 v66, v117, v243
	v_exp_f32_e32 v117, v66
	ds_read_b64_tr_b16 v[66:67], v247 offset:58368
	ds_read_b64_tr_b16 v[68:69], v247 offset:58880
	s_waitcnt lgkmcnt(6)
	v_mfma_f32_32x32x16_bf16 v[50:65], v[158:161], v[70:73], v[50:65]
	v_sub_f32_e32 v70, v118, v243
	v_exp_f32_e32 v118, v70
	v_sub_f32_e32 v70, v119, v243
	v_exp_f32_e32 v119, v70
	ds_read_b64_tr_b16 v[70:71], v247 offset:61440
	ds_read_b64_tr_b16 v[72:73], v247 offset:61952
	s_waitcnt lgkmcnt(6)
	v_mfma_f32_32x32x16_bf16 v[50:65], v[154:157], v[74:77], v[50:65]
	v_sub_f32_e32 v74, v120, v243
	v_exp_f32_e32 v120, v74
	v_sub_f32_e32 v74, v121, v243
	v_exp_f32_e32 v121, v74
	ds_read_b64_tr_b16 v[74:75], v247 offset:62464
	ds_read_b64_tr_b16 v[76:77], v247 offset:62976
	s_waitcnt lgkmcnt(6)
	v_mfma_f32_32x32x16_bf16 v[34:49], v[158:161], v[78:81], v[34:49]
	v_sub_f32_e32 v78, v122, v243
	v_exp_f32_e32 v122, v78
	v_sub_f32_e32 v78, v123, v243
	v_exp_f32_e32 v123, v78
	ds_read_b64_tr_b16 v[78:79], v247 offset:51200
	ds_read_b64_tr_b16 v[80:81], v247 offset:51712
	s_waitcnt lgkmcnt(6)
	v_mfma_f32_32x32x16_bf16 v[34:49], v[154:157], v[66:69], v[34:49]
	v_sub_f32_e32 v66, v124, v243
	v_exp_f32_e32 v124, v66
	v_sub_f32_e32 v66, v125, v243
	v_exp_f32_e32 v125, v66
	ds_read_b64_tr_b16 v[82:83], v247 offset:52224
	ds_read_b64_tr_b16 v[84:85], v247 offset:52736
	s_waitcnt lgkmcnt(6)
	v_mfma_f32_32x32x16_bf16 v[2:17], v[158:161], v[70:73], v[2:17]
	v_sub_f32_e32 v66, v126, v243
	v_exp_f32_e32 v126, v66
	v_sub_f32_e32 v66, v127, v243
	v_exp_f32_e32 v127, v66
	ds_read_b64_tr_b16 v[86:87], v247 offset:55296
	ds_read_b64_tr_b16 v[88:89], v247 offset:55808
	s_waitcnt lgkmcnt(6)
	v_mfma_f32_32x32x16_bf16 v[2:17], v[154:157], v[74:77], v[2:17]
	v_sub_f32_e32 v66, v128, v243
	v_exp_f32_e32 v128, v66
	v_sub_f32_e32 v66, v129, v243
	v_exp_f32_e32 v129, v66
	ds_read_b64_tr_b16 v[74:75], v247 offset:56320
	ds_read_b64_tr_b16 v[76:77], v247 offset:56832
	v_add_u32_e32 v90, s29, v245
	ds_read_b128 v[70:73], v90
	ds_read_b128 v[66:69], v90 offset:512
	s_waitcnt lgkmcnt(8)
	v_mfma_f32_32x32x16_bf16 v[18:33], v[138:141], v[78:81], v[18:33]
	v_sub_f32_e32 v78, v98, v243
	v_exp_f32_e32 v98, v78
	v_sub_f32_e32 v78, v99, v243
	v_exp_f32_e32 v99, v78
	ds_read_b64_tr_b16 v[78:79], v247 offset:59392
	ds_read_b64_tr_b16 v[80:81], v247 offset:59904
	ds_read_b128 v[182:185], v90 offset:2048
	ds_read_b128 v[174:177], v90 offset:2560
	s_waitcnt lgkmcnt(10)
	v_mfma_f32_32x32x16_bf16 v[18:33], v[130:133], v[82:85], v[18:33]
	v_sub_f32_e32 v82, v100, v243
	v_exp_f32_e32 v100, v82
	v_sub_f32_e32 v82, v101, v243
	v_exp_f32_e32 v101, v82
	ds_read_b64_tr_b16 v[82:83], v247 offset:60416
	ds_read_b64_tr_b16 v[84:85], v247 offset:60928
	ds_read_b128 v[178:181], v90 offset:4096
	ds_read_b128 v[166:169], v90 offset:4608
	s_waitcnt lgkmcnt(12)
	v_mfma_f32_32x32x16_bf16 v[50:65], v[138:141], v[86:89], v[50:65]
	v_sub_f32_e32 v86, v102, v243
	v_exp_f32_e32 v102, v86
	v_sub_f32_e32 v86, v103, v243
	v_exp_f32_e32 v103, v86
	ds_read_b64_tr_b16 v[86:87], v247 offset:63488
	ds_read_b64_tr_b16 v[88:89], v247 offset:64000
	ds_read_b128 v[170:173], v90 offset:6144
	ds_read_b128 v[162:165], v90 offset:6656
	s_waitcnt lgkmcnt(14)
	v_mfma_f32_32x32x16_bf16 v[50:65], v[130:133], v[74:77], v[50:65]
	v_sub_f32_e32 v74, v104, v243
	v_exp_f32_e32 v104, v74
	v_sub_f32_e32 v74, v105, v243
	v_exp_f32_e32 v105, v74
	ds_read_b64_tr_b16 v[74:75], v247 offset:64512
	ds_read_b64_tr_b16 v[76:77], v247 offset:65024
	s_waitcnt lgkmcnt(12)
	v_mfma_f32_32x32x16_bf16 v[34:49], v[138:141], v[78:81], v[34:49]
	v_sub_f32_e32 v78, v106, v243
	v_exp_f32_e32 v106, v78
	v_sub_f32_e32 v78, v107, v243
	v_exp_f32_e32 v107, v78
	s_waitcnt lgkmcnt(8)
	v_mfma_f32_32x32x16_bf16 v[34:49], v[130:133], v[82:85], v[34:49]
	v_sub_f32_e32 v78, v108, v243
	v_exp_f32_e32 v108, v78
	v_sub_f32_e32 v78, v109, v243
	v_exp_f32_e32 v109, v78
	s_waitcnt lgkmcnt(4)
	v_mfma_f32_32x32x16_bf16 v[2:17], v[138:141], v[86:89], v[2:17]
	v_sub_f32_e32 v78, v110, v243
	v_exp_f32_e32 v110, v78
	v_sub_f32_e32 v78, v111, v243
	v_exp_f32_e32 v111, v78
	s_waitcnt lgkmcnt(0)
	v_mfma_f32_32x32x16_bf16 v[2:17], v[130:133], v[74:77], v[2:17]
	v_sub_f32_e32 v74, v112, v243
	v_exp_f32_e32 v112, v74
	v_sub_f32_e32 v74, v113, v243
	v_exp_f32_e32 v113, v74
	s_waitcnt vmcnt(4) lgkmcnt(0)
	s_barrier
	s_andn2_b64 vcc, exec, s[36:37]
	s_cbranch_vccnz .LBB0_1312
	s_waitcnt lgkmcnt(0)
	ds_read_b128 v[74:77], v213 offset:96
	ds_read_b128 v[78:81], v213 offset:64
	ds_read_b128 v[82:85], v213 offset:32
	ds_read_b128 v[86:89], v213
	s_waitcnt lgkmcnt(3)
	v_pk_mul_f32 v[30:31], v[30:31], v[74:75]
	s_waitcnt lgkmcnt(2)
	v_pk_mul_f32 v[26:27], v[26:27], v[78:79]
	s_waitcnt lgkmcnt(1)
	v_pk_mul_f32 v[22:23], v[22:23], v[82:83]
	v_pk_mul_f32 v[32:33], v[32:33], v[76:77]
	v_pk_mul_f32 v[28:29], v[28:29], v[80:81]
	v_pk_mul_f32 v[24:25], v[24:25], v[84:85]
	s_waitcnt lgkmcnt(0)
	v_pk_mul_f32 v[20:21], v[20:21], v[88:89]
	v_pk_mul_f32 v[18:19], v[18:19], v[86:87]
	v_pk_mul_f32 v[62:63], v[62:63], v[74:75]
	v_pk_mul_f32 v[58:59], v[58:59], v[78:79]
	v_pk_mul_f32 v[54:55], v[54:55], v[82:83]
	v_pk_mul_f32 v[64:65], v[64:65], v[76:77]
	v_pk_mul_f32 v[60:61], v[60:61], v[80:81]
	v_pk_mul_f32 v[56:57], v[56:57], v[84:85]
	v_pk_mul_f32 v[52:53], v[52:53], v[88:89]
	v_pk_mul_f32 v[50:51], v[50:51], v[86:87]
	v_pk_mul_f32 v[46:47], v[46:47], v[74:75]
	v_pk_mul_f32 v[42:43], v[42:43], v[78:79]
	v_pk_mul_f32 v[38:39], v[38:39], v[82:83]
	v_pk_mul_f32 v[48:49], v[48:49], v[76:77]
	v_pk_mul_f32 v[44:45], v[44:45], v[80:81]
	v_pk_mul_f32 v[40:41], v[40:41], v[84:85]
	v_pk_mul_f32 v[36:37], v[36:37], v[88:89]
	v_pk_mul_f32 v[34:35], v[34:35], v[86:87]
	v_pk_mul_f32 v[14:15], v[14:15], v[74:75]
	v_pk_mul_f32 v[10:11], v[10:11], v[78:79]
	v_pk_mul_f32 v[6:7], v[6:7], v[82:83]
	v_pk_mul_f32 v[16:17], v[16:17], v[76:77]
	v_pk_mul_f32 v[12:13], v[12:13], v[80:81]
	v_pk_mul_f32 v[8:9], v[8:9], v[84:85]
	v_pk_mul_f32 v[4:5], v[4:5], v[88:89]
	v_pk_mul_f32 v[2:3], v[2:3], v[86:87]
.LBB0_1312:
	s_add_i32 s27, s29, 0x4000
	s_cmpk_lg_u32 s29, 0x8000
	s_cselect_b32 s27, s27, 0
	v_mfma_f32_32x32x16_bf16 v[82:97], v[70:73], v[150:153], 0
	v_add_f32_e32 v74, v114, v115
	v_add_f32_e32 v74, v116, v74
	v_add_f32_e32 v74, v117, v74
	v_add_f32_e32 v74, v118, v74
	v_add_u32_e32 v247, s91, v246
	v_add_f32_e32 v74, v119, v74
	v_cvt_pk_bf16_f32 v158, v114, v115
	v_cvt_pk_bf16_f32 v159, v116, v117
	s_nop 0
	v_add_f32_e32 v70, v120, v74
	v_add_f32_e32 v70, v121, v70
	v_add_f32_e32 v70, v122, v70
	v_add_f32_e32 v114, v123, v70
	v_mfma_f32_32x32x16_bf16 v[66:81], v[66:69], v[150:153], 0
	v_cvt_pk_bf16_f32 v160, v118, v119
	v_cvt_pk_bf16_f32 v161, v120, v121
	v_mfma_f32_32x32x16_bf16 v[82:97], v[182:185], v[146:149], v[82:97]
	v_add_f32_e32 v114, v124, v114
	v_add_f32_e32 v114, v125, v114
	v_add_f32_e32 v114, v126, v114
	v_add_f32_e32 v114, v127, v114
	v_cvt_pk_bf16_f32 v154, v122, v123
	v_cvt_pk_bf16_f32 v155, v124, v125
	v_mfma_f32_32x32x16_bf16 v[66:81], v[174:177], v[146:149], v[66:81]
	v_add_f32_e32 v114, v128, v114
	v_add_f32_e32 v114, v129, v114
	v_add_f32_e32 v114, v98, v114
	v_add_f32_e32 v118, v99, v114
	v_cvt_pk_bf16_f32 v156, v126, v127
	v_cvt_pk_bf16_f32 v157, v128, v129
	ds_read_b64_tr_b16 v[114:115], v247 offset:49152
	ds_read_b64_tr_b16 v[116:117], v247 offset:49664
	v_mfma_f32_32x32x16_bf16 v[82:97], v[178:181], v[142:145], v[82:97]
	v_add_f32_e32 v118, v100, v118
	v_add_f32_e32 v118, v101, v118
	v_add_f32_e32 v118, v102, v118
	v_add_f32_e32 v118, v103, v118
	v_cvt_pk_bf16_f32 v138, v98, v99
	v_cvt_pk_bf16_f32 v139, v100, v101
	ds_read_b64_tr_b16 v[98:99], v247 offset:50176
	ds_read_b64_tr_b16 v[100:101], v247 offset:50688
	v_mfma_f32_32x32x16_bf16 v[66:81], v[166:169], v[142:145], v[66:81]
	v_add_f32_e32 v118, v104, v118
	v_add_f32_e32 v118, v105, v118
	v_add_f32_e32 v118, v106, v118
	v_add_f32_e32 v118, v107, v118
	v_cvt_pk_bf16_f32 v140, v102, v103
	v_cvt_pk_bf16_f32 v141, v104, v105
	ds_read_b64_tr_b16 v[102:103], v247 offset:53248
	ds_read_b64_tr_b16 v[104:105], v247 offset:53760
	v_mfma_f32_32x32x16_bf16 v[82:97], v[170:173], v[134:137], v[82:97]
	v_add_f32_e32 v118, v108, v118
	v_add_f32_e32 v118, v109, v118
	v_add_f32_e32 v118, v110, v118
	v_add_f32_e32 v118, v111, v118
	v_cvt_pk_bf16_f32 v130, v106, v107
	v_cvt_pk_bf16_f32 v131, v108, v109
	ds_read_b64_tr_b16 v[106:107], v247 offset:54272
	ds_read_b64_tr_b16 v[108:109], v247 offset:54784
	v_mfma_f32_32x32x16_bf16 v[66:81], v[162:165], v[134:137], v[66:81]
	v_add_f32_e32 v118, v112, v118
	v_add_f32_e32 v118, v113, v118
	v_add_f32_e32 v118, 0, v118
	v_cvt_pk_bf16_f32 v132, v110, v111
	v_cvt_pk_bf16_f32 v133, v112, v113
	s_mov_b64 s[30:31], 0x1dd40000
	v_lshl_add_u64 v[110:111], v[188:189], 0, s[30:31]
	s_add_i32 s36, s29, s25
	s_mov_b32 s30, m0
	s_mov_b32 m0, s36
	s_nop 0
	global_load_lds_dwordx4 v[110:111], off
	s_mov_b32 m0, s30
	s_mov_b64 s[30:31], 0x1dd40080
	v_lshl_add_u64 v[110:111], v[188:189], 0, s[30:31]
	s_add_i32 s30, s36, 0x2000
	s_mov_b32 s31, m0
	s_mov_b32 m0, s30
	s_nop 0
	global_load_lds_dwordx4 v[110:111], off
	s_mov_b32 m0, s31
	s_mov_b64 s[30:31], 0x25cc0000
	v_lshl_add_u64 v[110:111], v[186:187], 0, s[30:31]
	s_add_i32 s36, s27, s24
	s_mov_b32 s30, m0
	s_mov_b32 m0, s36
	s_nop 0
	global_load_lds_dwordx4 v[110:111], off
	s_mov_b32 m0, s30
	s_mov_b64 s[30:31], 0x25cc0080
	v_lshl_add_u64 v[110:111], v[186:187], 0, s[30:31]
	s_add_i32 s30, s36, 0x2000
	s_mov_b32 s31, m0
	s_mov_b32 m0, s30
	s_nop 0
	global_load_lds_dwordx4 v[110:111], off
	s_mov_b32 m0, s31
	v_max_f32_e32 v110, v83, v83
	v_max_f32_e32 v111, v82, v82
	v_max_f32_e32 v110, v111, v110
	v_max3_f32 v111, v84, v85, v67
	v_max3_f32 v110, v110, v66, v68
	v_max3_f32 v110, v110, v69, v86
	v_max3_f32 v111, v111, v88, v89
	v_max3_f32 v110, v110, v87, v70
	v_max3_f32 v111, v111, v72, v73
	v_max3_f32 v110, v110, v71, v90
	v_max3_f32 v111, v111, v92, v93
	v_max3_f32 v110, v110, v91, v74
	v_max3_f32 v111, v111, v76, v77
	v_max3_f32 v110, v110, v75, v94
	v_max3_f32 v111, v111, v96, v97
	v_max3_f32 v110, v110, v95, v78
	v_max3_f32 v111, v111, v80, v81
	v_max3_f32 v110, v110, v79, v111
	v_mov_b32_e32 v111, v110
	s_nop 1
	v_permlane32_swap_b32_e32 v110, v111
	v_max_f32_e32 v111, v111, v111
	v_max_f32_e32 v110, v110, v110
	v_max_f32_e32 v110, v110, v111
	v_sub_f32_e32 v110, v110, v243
	v_cmp_lt_f32_e32 vcc, s93, v110
	s_cmp_lg_u64 vcc, 0
	v_add_f32_e32 v250, v190, v118
	s_cselect_b64 s[36:37], -1, 0
	s_cbranch_vccnz .LBB0_1320
.LBB0_1313:
	s_waitcnt lgkmcnt(6)
	v_mfma_f32_32x32x16_bf16 v[18:33], v[158:161], v[114:117], v[18:33]
	v_sub_f32_e32 v82, v82, v243
	v_sub_f32_e32 v83, v83, v243
	v_exp_f32_e32 v82, v82
	v_exp_f32_e32 v83, v83
	ds_read_b64_tr_b16 v[110:111], v247 offset:57344
	ds_read_b64_tr_b16 v[112:113], v247 offset:57856
	s_waitcnt lgkmcnt(6)
	v_mfma_f32_32x32x16_bf16 v[18:33], v[154:157], v[98:101], v[18:33]
	v_sub_f32_e32 v84, v84, v243
	v_sub_f32_e32 v85, v85, v243
	v_exp_f32_e32 v84, v84
	v_exp_f32_e32 v85, v85
	ds_read_b64_tr_b16 v[98:99], v247 offset:58368
	ds_read_b64_tr_b16 v[100:101], v247 offset:58880
	s_waitcnt lgkmcnt(6)
	v_mfma_f32_32x32x16_bf16 v[50:65], v[158:161], v[102:105], v[50:65]
	v_sub_f32_e32 v86, v86, v243
	v_sub_f32_e32 v87, v87, v243
	v_exp_f32_e32 v86, v86
	v_exp_f32_e32 v87, v87
	ds_read_b64_tr_b16 v[102:103], v247 offset:61440
	ds_read_b64_tr_b16 v[104:105], v247 offset:61952
	s_waitcnt lgkmcnt(6)
	v_mfma_f32_32x32x16_bf16 v[50:65], v[154:157], v[106:109], v[50:65]
	v_sub_f32_e32 v88, v88, v243
	v_sub_f32_e32 v89, v89, v243
	v_exp_f32_e32 v88, v88
	v_exp_f32_e32 v89, v89
	ds_read_b64_tr_b16 v[106:107], v247 offset:62464
	ds_read_b64_tr_b16 v[108:109], v247 offset:62976
	s_waitcnt lgkmcnt(6)
	v_mfma_f32_32x32x16_bf16 v[34:49], v[158:161], v[110:113], v[34:49]
	v_sub_f32_e32 v90, v90, v243
	v_sub_f32_e32 v91, v91, v243
	v_exp_f32_e32 v90, v90
	v_exp_f32_e32 v91, v91
	ds_read_b64_tr_b16 v[110:111], v247 offset:51200
	ds_read_b64_tr_b16 v[112:113], v247 offset:51712
	s_waitcnt lgkmcnt(6)
	v_mfma_f32_32x32x16_bf16 v[34:49], v[154:157], v[98:101], v[34:49]
	v_sub_f32_e32 v92, v92, v243
	v_sub_f32_e32 v93, v93, v243
	v_exp_f32_e32 v92, v92
	v_exp_f32_e32 v93, v93
	ds_read_b64_tr_b16 v[98:99], v247 offset:52224
	ds_read_b64_tr_b16 v[100:101], v247 offset:52736
	s_waitcnt lgkmcnt(6)
	v_mfma_f32_32x32x16_bf16 v[2:17], v[158:161], v[102:105], v[2:17]
	v_sub_f32_e32 v94, v94, v243
	v_sub_f32_e32 v95, v95, v243
	v_exp_f32_e32 v94, v94
	v_exp_f32_e32 v95, v95
	ds_read_b64_tr_b16 v[102:103], v247 offset:55296
	ds_read_b64_tr_b16 v[104:105], v247 offset:55808
	s_waitcnt lgkmcnt(6)
	v_mfma_f32_32x32x16_bf16 v[2:17], v[154:157], v[106:109], v[2:17]
	v_sub_f32_e32 v96, v96, v243
	v_sub_f32_e32 v97, v97, v243
	v_exp_f32_e32 v96, v96
	v_exp_f32_e32 v97, v97
	ds_read_b64_tr_b16 v[106:107], v247 offset:56320
	ds_read_b64_tr_b16 v[108:109], v247 offset:56832
	v_add_u32_e32 v114, s27, v245
	ds_read_b128 v[190:193], v114
	ds_read_b128 v[182:185], v114 offset:512
	s_waitcnt lgkmcnt(8)
	v_mfma_f32_32x32x16_bf16 v[18:33], v[138:141], v[110:113], v[18:33]
	v_sub_f32_e32 v66, v66, v243
	v_sub_f32_e32 v67, v67, v243
	v_exp_f32_e32 v66, v66
	v_exp_f32_e32 v67, v67
	ds_read_b64_tr_b16 v[110:111], v247 offset:59392
	ds_read_b64_tr_b16 v[112:113], v247 offset:59904
	ds_read_b128 v[186:189], v114 offset:2048
	ds_read_b128 v[178:181], v114 offset:2560
	s_waitcnt lgkmcnt(10)
	v_mfma_f32_32x32x16_bf16 v[18:33], v[130:133], v[98:101], v[18:33]
	v_sub_f32_e32 v68, v68, v243
	v_sub_f32_e32 v69, v69, v243
	v_exp_f32_e32 v68, v68
	v_exp_f32_e32 v69, v69
	ds_read_b64_tr_b16 v[98:99], v247 offset:60416
	ds_read_b64_tr_b16 v[100:101], v247 offset:60928
	ds_read_b128 v[174:177], v114 offset:4096
	ds_read_b128 v[170:173], v114 offset:4608
	s_waitcnt lgkmcnt(12)
	v_mfma_f32_32x32x16_bf16 v[50:65], v[138:141], v[102:105], v[50:65]
	v_sub_f32_e32 v70, v70, v243
	v_sub_f32_e32 v71, v71, v243
	v_exp_f32_e32 v70, v70
	v_exp_f32_e32 v71, v71
	ds_read_b64_tr_b16 v[102:103], v247 offset:63488
	ds_read_b64_tr_b16 v[104:105], v247 offset:64000
	ds_read_b128 v[166:169], v114 offset:6144
	ds_read_b128 v[162:165], v114 offset:6656
	s_waitcnt lgkmcnt(14)
	v_mfma_f32_32x32x16_bf16 v[50:65], v[130:133], v[106:109], v[50:65]
	v_sub_f32_e32 v72, v72, v243
	v_sub_f32_e32 v73, v73, v243
	v_exp_f32_e32 v72, v72
	v_exp_f32_e32 v73, v73
	ds_read_b64_tr_b16 v[106:107], v247 offset:64512
	ds_read_b64_tr_b16 v[108:109], v247 offset:65024
	s_waitcnt lgkmcnt(12)
	v_mfma_f32_32x32x16_bf16 v[34:49], v[138:141], v[110:113], v[34:49]
	v_sub_f32_e32 v74, v74, v243
	v_sub_f32_e32 v75, v75, v243
	v_exp_f32_e32 v74, v74
	v_exp_f32_e32 v75, v75
	s_waitcnt lgkmcnt(8)
	v_mfma_f32_32x32x16_bf16 v[34:49], v[130:133], v[98:101], v[34:49]
	v_sub_f32_e32 v76, v76, v243
	v_sub_f32_e32 v77, v77, v243
	v_exp_f32_e32 v76, v76
	v_exp_f32_e32 v77, v77
	s_waitcnt lgkmcnt(4)
	v_mfma_f32_32x32x16_bf16 v[2:17], v[138:141], v[102:105], v[2:17]
	v_sub_f32_e32 v78, v78, v243
	v_sub_f32_e32 v79, v79, v243
	v_exp_f32_e32 v78, v78
	v_exp_f32_e32 v79, v79
	s_waitcnt lgkmcnt(0)
	v_mfma_f32_32x32x16_bf16 v[2:17], v[130:133], v[106:109], v[2:17]
	v_sub_f32_e32 v80, v80, v243
	v_sub_f32_e32 v81, v81, v243
	v_exp_f32_e32 v80, v80
	v_exp_f32_e32 v81, v81
	s_waitcnt vmcnt(4) lgkmcnt(0)
	s_barrier
	s_andn2_b64 vcc, exec, s[36:37]
	s_cbranch_vccnz .LBB0_1315
	s_waitcnt lgkmcnt(0)
	ds_read_b128 v[98:101], v213 offset:96
	ds_read_b128 v[102:105], v213 offset:64
	ds_read_b128 v[106:109], v213 offset:32
	ds_read_b128 v[110:113], v213
	s_waitcnt lgkmcnt(3)
	v_pk_mul_f32 v[30:31], v[30:31], v[98:99]
	s_waitcnt lgkmcnt(2)
	v_pk_mul_f32 v[26:27], v[26:27], v[102:103]
	s_waitcnt lgkmcnt(1)
	v_pk_mul_f32 v[22:23], v[22:23], v[106:107]
	v_pk_mul_f32 v[32:33], v[32:33], v[100:101]
	v_pk_mul_f32 v[28:29], v[28:29], v[104:105]
	v_pk_mul_f32 v[24:25], v[24:25], v[108:109]
	s_waitcnt lgkmcnt(0)
	v_pk_mul_f32 v[20:21], v[20:21], v[112:113]
	v_pk_mul_f32 v[18:19], v[18:19], v[110:111]
	v_pk_mul_f32 v[62:63], v[62:63], v[98:99]
	v_pk_mul_f32 v[58:59], v[58:59], v[102:103]
	v_pk_mul_f32 v[54:55], v[54:55], v[106:107]
	v_pk_mul_f32 v[64:65], v[64:65], v[100:101]
	v_pk_mul_f32 v[60:61], v[60:61], v[104:105]
	v_pk_mul_f32 v[56:57], v[56:57], v[108:109]
	v_pk_mul_f32 v[52:53], v[52:53], v[112:113]
	v_pk_mul_f32 v[50:51], v[50:51], v[110:111]
	v_pk_mul_f32 v[46:47], v[46:47], v[98:99]
	v_pk_mul_f32 v[42:43], v[42:43], v[102:103]
	v_pk_mul_f32 v[38:39], v[38:39], v[106:107]
	v_pk_mul_f32 v[48:49], v[48:49], v[100:101]
	v_pk_mul_f32 v[44:45], v[44:45], v[104:105]
	v_pk_mul_f32 v[40:41], v[40:41], v[108:109]
	v_pk_mul_f32 v[36:37], v[36:37], v[112:113]
	v_pk_mul_f32 v[34:35], v[34:35], v[110:111]
	v_pk_mul_f32 v[14:15], v[14:15], v[98:99]
	v_pk_mul_f32 v[10:11], v[10:11], v[102:103]
	v_pk_mul_f32 v[6:7], v[6:7], v[106:107]
	v_pk_mul_f32 v[16:17], v[16:17], v[100:101]
	v_pk_mul_f32 v[12:13], v[12:13], v[104:105]
	v_pk_mul_f32 v[8:9], v[8:9], v[108:109]
	v_pk_mul_f32 v[4:5], v[4:5], v[112:113]
	v_pk_mul_f32 v[2:3], v[2:3], v[110:111]
